# v19 + hand-written sample-gMLP task: all loads up front behind one wait, LayerNorm stats per wave via readlane (no LDS/barriers), same f32 math order
# baseline (speedup 1.0000x reference)
.LBB0_409:
	s_add_i32 s0, s55, s46
	s_cmp_ge_i32 s0, s35
	s_cselect_b32 s1, s35, 0
	s_sub_i32 s0, s0, s1
	s_mul_i32 s56, s0, s3
	s_add_i32 s56, s56, s2
	s_cmpk_gt_i32 s56, 0xd7f
	s_cbranch_scc1 .LBB0_408
	s_cmpk_gt_i32 s56, 0x2ff
	s_mov_b64 s[0:1], -1
	s_cbranch_scc0 .LBB0_1037
	s_cmpk_gt_u32 s56, 0x4ff
	s_cbranch_scc0 .LBB0_1034
	s_cmpk_gt_u32 s56, 0x7ff
	s_cbranch_scc0 .LBB0_1021
	s_cmpk_gt_u32 s56, 0xcff
	s_cbranch_scc0 .LBB0_419
	v_readfirstlane_b32 s1, v192
	s_cmp_ge_u32 s1, 0x180
	s_cbranch_scc1 .Lsg_done
	s_lshr_b32 s1, s1, 6
	s_add_i32 s0, s56, 0xfffff300
	s_mul_i32 s14, s0, 0x1800
	s_add_u32 s4, s38, 0x4601a00
	s_addc_u32 s5, s39, 0
	s_add_u32 s4, s4, s14
	s_addc_u32 s5, s5, 0
	s_add_u32 s6, s38, 0x3941a00
	s_addc_u32 s7, s39, 0
	s_add_u32 s6, s6, s14
	s_addc_u32 s7, s7, 0
	s_add_u32 s8, s38, 0x538da00
	s_addc_u32 s9, s39, 0
	s_add_u32 s8, s8, s14
	s_addc_u32 s9, s9, 0
	s_lshl_b32 s14, s14, 1
	s_add_u32 s10, s36, 0x19a40000
	s_addc_u32 s11, s37, 0
	s_add_u32 s10, s10, s14
	s_addc_u32 s11, s11, 0
	s_lshl_b32 s14, s0, 14
	s_add_u32 s12, s38, 0xc5b3a00
	s_addc_u32 s13, s39, 0
	s_add_u32 s12, s12, s14
	s_addc_u32 s13, s13, 0
	s_mul_i32 s14, s0, 0x180
	s_add_u32 s16, s38, 0x4781a00
	s_addc_u32 s17, s39, 0
	s_add_u32 s16, s16, s14
	s_addc_u32 s17, s17, 0
	v_and_b32_e32 v114, 7, v192
	v_mul_u32_u24_e32 v114, 48, v114
	v_lshlrev_b32_e32 v112, 1, v192
	v_lshlrev_b32_e32 v113, 2, v192
	v_mov_b32_e32 v115, 0
	global_load_dwordx4 v[0:3], v114, s[16:17]
	global_load_dwordx4 v[4:7], v114, s[16:17] offset:16
	global_load_dwordx4 v[8:11], v114, s[16:17] offset:32
	v_readlane_b32 s14, v255, 14
	v_readlane_b32 s15, v255, 15
	s_nop 4
	global_load_dword v12, v113, s[14:15]
	v_readlane_b32 s14, v255, 16
	v_readlane_b32 s15, v255, 17
	s_nop 4
	global_load_dword v13, v113, s[14:15]
	s_add_u32 s16, s4, 0xc00
	s_addc_u32 s17, s5, 0
	global_load_ushort v14, v112, s[4:5]
	global_load_ushort v15, v112, s[4:5] offset:768
	global_load_ushort v16, v112, s[4:5] offset:1536
	global_load_ushort v17, v112, s[4:5] offset:2304
	global_load_ushort v18, v112, s[16:17]
	global_load_ushort v19, v112, s[16:17] offset:768
	global_load_ushort v20, v112, s[16:17] offset:1536
	global_load_ushort v21, v112, s[16:17] offset:2304
	v_readlane_b32 s14, v255, 18
	v_readlane_b32 s15, v255, 19
	s_lshl_b32 s16, s1, 16
	s_add_u32 s14, s14, s16
	s_addc_u32 s15, s15, 0
	global_load_dwordx4 v[40:43], v115, s[14:15]
	global_load_dwordx4 v[48:51], v115, s[14:15] offset:512
	global_load_dwordx4 v[56:59], v115, s[14:15] offset:1024
	global_load_dwordx4 v[64:67], v115, s[14:15] offset:1536
	global_load_dwordx4 v[72:75], v115, s[14:15] offset:2048
	global_load_dwordx4 v[76:79], v115, s[14:15] offset:2064
	global_load_dwordx4 v[80:83], v115, s[14:15] offset:2560
	global_load_dwordx4 v[84:87], v115, s[14:15] offset:2576
	global_load_dwordx4 v[88:91], v115, s[14:15] offset:3072
	global_load_dwordx4 v[92:95], v115, s[14:15] offset:3088
	global_load_dwordx4 v[96:99], v115, s[14:15] offset:3584
	global_load_dwordx4 v[100:103], v115, s[14:15] offset:3600
	v_readlane_b32 s14, v255, 20
	v_readlane_b32 s15, v255, 21
	s_lshl_b32 s16, s1, 9
	s_add_u32 s14, s14, s16
	s_addc_u32 s15, s15, 0
	global_load_dwordx4 v[104:107], v115, s[14:15]
	global_load_dwordx4 v[108:111], v115, s[14:15] offset:16
	s_add_u32 s14, s6, 0xc00
	s_addc_u32 s15, s7, 0
	s_add_u32 s16, s8, 0xc00
	s_addc_u32 s17, s9, 0
	global_load_ushort v22, v112, s[6:7]
	global_load_ushort v30, v112, s[8:9]
	global_load_ushort v23, v112, s[6:7] offset:768
	global_load_ushort v31, v112, s[8:9] offset:768
	global_load_ushort v24, v112, s[6:7] offset:1536
	global_load_ushort v32, v112, s[8:9] offset:1536
	global_load_ushort v25, v112, s[6:7] offset:2304
	global_load_ushort v33, v112, s[8:9] offset:2304
	global_load_ushort v26, v112, s[14:15]
	global_load_ushort v34, v112, s[16:17]
	global_load_ushort v27, v112, s[14:15] offset:768
	global_load_ushort v35, v112, s[16:17] offset:768
	global_load_ushort v28, v112, s[14:15] offset:1536
	global_load_ushort v36, v112, s[16:17] offset:1536
	global_load_ushort v29, v112, s[14:15] offset:2304
	global_load_ushort v37, v112, s[16:17] offset:2304
	s_waitcnt vmcnt(40)
	v_pk_add_f32 v[0:1], v[0:1], v[2:3]
	s_nop 0
	v_pk_add_f32 v[0:1], v[0:1], v[4:5]
	s_nop 0
	v_pk_add_f32 v[0:1], v[0:1], v[6:7]
	s_nop 0
	v_pk_add_f32 v[0:1], v[0:1], v[8:9]
	s_nop 0
	v_pk_add_f32 v[0:1], v[0:1], v[10:11]
	s_nop 0
	v_mul_f32_e32 v0, 0x3b2aaaab, v0
	v_mul_f32_e32 v1, 0x3b2aaaab, v1
	v_fma_f32 v1, -v0, v0, v1
	v_max_f32_e32 v1, 0, v1
	v_add_f32_e32 v1, 0x358637bd, v1
	v_rsq_f32_e32 v1, v1
	s_nop 1
	v_readlane_b32 s16, v0, 0
	v_readlane_b32 s17, v1, 0
	v_readlane_b32 s18, v0, 1
	v_readlane_b32 s19, v1, 1
	v_readlane_b32 s20, v0, 2
	v_readlane_b32 s21, v1, 2
	v_readlane_b32 s22, v0, 3
	v_readlane_b32 s23, v1, 3
	v_readlane_b32 s24, v0, 4
	v_readlane_b32 s25, v1, 4
	v_readlane_b32 s26, v0, 5
	v_readlane_b32 s27, v1, 5
	v_readlane_b32 s28, v0, 6
	v_readlane_b32 s29, v1, 6
	v_readlane_b32 s30, v0, 7
	v_readlane_b32 s31, v1, 7
	s_waitcnt vmcnt(0)
	v_lshlrev_b32_e32 v124, 16, v14
	v_subrev_f32_e32 v124, s16, v124
	v_mul_f32_e32 v124, s17, v124
	v_fma_f32 v116, v12, v124, v13
	v_lshlrev_b32_e32 v124, 16, v15
	v_subrev_f32_e32 v124, s18, v124
	v_mul_f32_e32 v124, s19, v124
	v_fma_f32 v117, v12, v124, v13
	v_lshlrev_b32_e32 v124, 16, v16
	v_subrev_f32_e32 v124, s20, v124
	v_mul_f32_e32 v124, s21, v124
	v_fma_f32 v118, v12, v124, v13
	v_lshlrev_b32_e32 v124, 16, v17
	v_subrev_f32_e32 v124, s22, v124
	v_mul_f32_e32 v124, s23, v124
	v_fma_f32 v119, v12, v124, v13
	v_lshlrev_b32_e32 v124, 16, v18
	v_subrev_f32_e32 v124, s24, v124
	v_mul_f32_e32 v124, s25, v124
	v_fma_f32 v120, v12, v124, v13
	v_lshlrev_b32_e32 v124, 16, v19
	v_subrev_f32_e32 v124, s26, v124
	v_mul_f32_e32 v124, s27, v124
	v_fma_f32 v121, v12, v124, v13
	v_lshlrev_b32_e32 v124, 16, v20
	v_subrev_f32_e32 v124, s28, v124
	v_mul_f32_e32 v124, s29, v124
	v_fma_f32 v122, v12, v124, v13
	v_lshlrev_b32_e32 v124, 16, v21
	v_subrev_f32_e32 v124, s30, v124
	v_mul_f32_e32 v124, s31, v124
	v_fma_f32 v123, v12, v124, v13
	global_store_dword v113, v116, s[10:11]
	global_store_dword v113, v117, s[10:11] offset:1536
	s_add_u32 s10, s10, 0xc00
	s_addc_u32 s11, s11, 0
	global_store_dword v113, v118, s[10:11]
	global_store_dword v113, v119, s[10:11] offset:1536
	s_add_u32 s10, s10, 0xc00
	s_addc_u32 s11, s11, 0
	global_store_dword v113, v120, s[10:11]
	global_store_dword v113, v121, s[10:11] offset:1536
	s_add_u32 s10, s10, 0xc00
	s_addc_u32 s11, s11, 0
	global_store_dword v113, v122, s[10:11]
	global_store_dword v113, v123, s[10:11] offset:1536
	v_fmac_f32_e32 v104, v116, v40
	v_lshlrev_b32_e32 v124, 16, v22
	v_lshlrev_b32_e32 v125, 16, v30
	v_mul_f32_e32 v104, v104, v124
	v_mul_f32_e32 v104, v104, v125
	v_cvt_pk_bf16_f32 v104, v104, v104
	global_store_short v112, v104, s[12:13]
	v_fmac_f32_e32 v105, v116, v48
	v_fmac_f32_e32 v105, v117, v49
	v_lshlrev_b32_e32 v124, 16, v23
	v_lshlrev_b32_e32 v125, 16, v31
	v_mul_f32_e32 v105, v105, v124
	v_mul_f32_e32 v105, v105, v125
	v_cvt_pk_bf16_f32 v105, v105, v105
	global_store_short v112, v105, s[12:13] offset:2048
	s_add_u32 s12, s12, 0x1000
	s_addc_u32 s13, s13, 0
	v_fmac_f32_e32 v106, v116, v56
	v_fmac_f32_e32 v106, v117, v57
	v_fmac_f32_e32 v106, v118, v58
	v_lshlrev_b32_e32 v124, 16, v24
	v_lshlrev_b32_e32 v125, 16, v32
	v_mul_f32_e32 v106, v106, v124
	v_mul_f32_e32 v106, v106, v125
	v_cvt_pk_bf16_f32 v106, v106, v106
	global_store_short v112, v106, s[12:13]
	v_fmac_f32_e32 v107, v116, v64
	v_fmac_f32_e32 v107, v117, v65
	v_fmac_f32_e32 v107, v118, v66
	v_fmac_f32_e32 v107, v119, v67
	v_lshlrev_b32_e32 v124, 16, v25
	v_lshlrev_b32_e32 v125, 16, v33
	v_mul_f32_e32 v107, v107, v124
	v_mul_f32_e32 v107, v107, v125
	v_cvt_pk_bf16_f32 v107, v107, v107
	global_store_short v112, v107, s[12:13] offset:2048
	s_add_u32 s12, s12, 0x1000
	s_addc_u32 s13, s13, 0
	v_fmac_f32_e32 v108, v116, v72
	v_fmac_f32_e32 v108, v117, v73
	v_fmac_f32_e32 v108, v118, v74
	v_fmac_f32_e32 v108, v119, v75
	v_fmac_f32_e32 v108, v120, v76
	v_lshlrev_b32_e32 v124, 16, v26
	v_lshlrev_b32_e32 v125, 16, v34
	v_mul_f32_e32 v108, v108, v124
	v_mul_f32_e32 v108, v108, v125
	v_cvt_pk_bf16_f32 v108, v108, v108
	global_store_short v112, v108, s[12:13]
	v_fmac_f32_e32 v109, v116, v80
	v_fmac_f32_e32 v109, v117, v81
	v_fmac_f32_e32 v109, v118, v82
	v_fmac_f32_e32 v109, v119, v83
	v_fmac_f32_e32 v109, v120, v84
	v_fmac_f32_e32 v109, v121, v85
	v_lshlrev_b32_e32 v124, 16, v27
	v_lshlrev_b32_e32 v125, 16, v35
	v_mul_f32_e32 v109, v109, v124
	v_mul_f32_e32 v109, v109, v125
	v_cvt_pk_bf16_f32 v109, v109, v109
	global_store_short v112, v109, s[12:13] offset:2048
	s_add_u32 s12, s12, 0x1000
	s_addc_u32 s13, s13, 0
	v_fmac_f32_e32 v110, v116, v88
	v_fmac_f32_e32 v110, v117, v89
	v_fmac_f32_e32 v110, v118, v90
	v_fmac_f32_e32 v110, v119, v91
	v_fmac_f32_e32 v110, v120, v92
	v_fmac_f32_e32 v110, v121, v93
	v_fmac_f32_e32 v110, v122, v94
	v_lshlrev_b32_e32 v124, 16, v28
	v_lshlrev_b32_e32 v125, 16, v36
	v_mul_f32_e32 v110, v110, v124
	v_mul_f32_e32 v110, v110, v125
	v_cvt_pk_bf16_f32 v110, v110, v110
	global_store_short v112, v110, s[12:13]
	v_fmac_f32_e32 v111, v116, v96
	v_fmac_f32_e32 v111, v117, v97
	v_fmac_f32_e32 v111, v118, v98
	v_fmac_f32_e32 v111, v119, v99
	v_fmac_f32_e32 v111, v120, v100
	v_fmac_f32_e32 v111, v121, v101
	v_fmac_f32_e32 v111, v122, v102
	v_fmac_f32_e32 v111, v123, v103
	v_lshlrev_b32_e32 v124, 16, v29
	v_lshlrev_b32_e32 v125, 16, v37
	v_mul_f32_e32 v111, v111, v124
	v_mul_f32_e32 v111, v111, v125
	v_cvt_pk_bf16_f32 v111, v111, v111
	global_store_short v112, v111, s[12:13] offset:2048
.Lsg_done:
	s_mov_b64 s[0:1], exec
.LBB0_418:
	s_or_b64 exec, exec, s[0:1]
	s_mov_b64 s[0:1], 0
